# attention QK section: first row-max op deferred behind the remaining MFMAs so one 11-state MFMA-result pad disappears
# baseline (speedup 1.0000x reference)
; #define MFMA32(a, b, c) __builtin_amdgcn_mfma_f32_32x32x16_bf16((a), (b), (c), 0, 0, 0)
; __device__ __forceinline__ void attn_unit2(const bf16_t* Qm, const bf16_t* KVm, const bf16_t* P1, bf16_t* OP, int q0, int h, int klat, int nlat, int kctx, int nt, uchar* lds, bool nostore = false) {
;     ...
;         { const uchar* kb = Kt + buf * KT_BYTES + l32 * KROW + hi * 16;
; #pragma unroll
;           for (int s = 0; s < 6; ++s) { const bf16x8 a0 = *(const bf16x8*)(kb + s * 32), a1 = *(const bf16x8*)(kb + 32 * KROW + s * 32);
;               sA0 = MFMA32(a0, qa[s], sA0); sA1 = MFMA32(a1, qa[s], sA1); sB0 = MFMA32(a0, qb[s], sB0); sB1 = MFMA32(a1, qb[s], sB1); } }
.LBB0_1117:
	s_and_b32 s4, s9, 1
	s_mul_i32 s5, s4, 0x3400
	v_add_u32_e32 v0, s5, v226
	ds_read_b128 v[66:69], v0
	ds_read_b128 v[70:73], v0 offset:32
	ds_read_b128 v[74:77], v0 offset:6656
	ds_read_b128 v[234:237], v0 offset:6688
	v_mfma_f32_32x32x16_bf16 v[114:129], v[208:211], v[216:219], 0
	v_mfma_f32_32x32x16_bf16 v[98:113], v[208:211], v[190:193], 0
	s_waitcnt lgkmcnt(3)
	v_mfma_f32_32x32x16_bf16 v[114:129], v[66:69], v[130:133], v[114:129]
	v_mfma_f32_32x32x16_bf16 v[98:113], v[66:69], v[170:173], v[98:113]
	s_waitcnt lgkmcnt(2)
	v_mfma_f32_32x32x16_bf16 v[114:129], v[70:73], v[134:137], v[114:129]
	v_mfma_f32_32x32x16_bf16 v[98:113], v[70:73], v[138:141], v[98:113]
	ds_read_b128 v[66:69], v0 offset:64
	ds_read_b128 v[70:73], v0 offset:96
	ds_read_b128 v[238:241], v0 offset:6720
	ds_read_b128 v[242:245], v0 offset:6752
	s_waitcnt lgkmcnt(3)
	v_mfma_f32_32x32x16_bf16 v[114:129], v[66:69], v[146:149], v[114:129]
	v_mfma_f32_32x32x16_bf16 v[98:113], v[66:69], v[142:145], v[98:113]
	v_mfma_f32_32x32x16_bf16 v[82:97], v[208:211], v[216:219], 0
	v_mfma_f32_32x32x16_bf16 v[82:97], v[74:77], v[130:133], v[82:97]
	s_waitcnt lgkmcnt(2)
	v_mfma_f32_32x32x16_bf16 v[114:129], v[70:73], v[150:153], v[114:129]
	v_mfma_f32_32x32x16_bf16 v[98:113], v[70:73], v[154:157], v[98:113]
	ds_read_b128 v[66:69], v0 offset:128
	ds_read_b128 v[70:73], v0 offset:160
	ds_read_b128 v[246:249], v0 offset:6784
	ds_read_b128 v[212:215], v0 offset:6816
	v_mfma_f32_32x32x16_bf16 v[82:97], v[234:237], v[134:137], v[82:97]
	s_waitcnt lgkmcnt(3)
	v_mfma_f32_32x32x16_bf16 v[114:129], v[66:69], v[162:165], v[114:129]
	v_mfma_f32_32x32x16_bf16 v[98:113], v[66:69], v[158:161], v[98:113]
	v_mfma_f32_32x32x16_bf16 v[82:97], v[238:241], v[146:149], v[82:97]
	s_waitcnt lgkmcnt(2)
	v_mfma_f32_32x32x16_bf16 v[114:129], v[70:73], v[166:169], v[114:129]
	v_mfma_f32_32x32x16_bf16 v[98:113], v[70:73], v[174:177], v[98:113]
	v_mfma_f32_32x32x16_bf16 v[66:81], v[74:77], v[170:173], 0
	v_mfma_f32_32x32x16_bf16 v[66:81], v[208:211], v[190:193], v[66:81]
	v_mfma_f32_32x32x16_bf16 v[82:97], v[242:245], v[150:153], v[82:97]
	v_mfma_f32_32x32x16_bf16 v[66:81], v[234:237], v[138:141], v[66:81]
	s_waitcnt lgkmcnt(1)
	v_mfma_f32_32x32x16_bf16 v[82:97], v[246:249], v[162:165], v[82:97]
	v_mfma_f32_32x32x16_bf16 v[66:81], v[238:241], v[142:145], v[66:81]
	s_waitcnt lgkmcnt(0)
	v_mfma_f32_32x32x16_bf16 v[82:97], v[212:215], v[166:169], v[82:97]
	v_mfma_f32_32x32x16_bf16 v[66:81], v[242:245], v[154:157], v[66:81]
	s_nop 10
	v_max_f32_e32 v0, v114, v115
	v_max3_f32 v234, v116, v117, v83
	v_max3_f32 v0, v0, v82, v84
	v_max3_f32 v0, v0, v85, v118
	v_max3_f32 v234, v234, v120, v121
	v_max3_f32 v0, v0, v119, v86
	v_max3_f32 v234, v234, v88, v89
	v_max3_f32 v0, v0, v87, v122
	v_mfma_f32_32x32x16_bf16 v[66:81], v[246:249], v[158:161], v[66:81]
	v_mfma_f32_32x32x16_bf16 v[66:81], v[212:215], v[174:177], v[66:81]
	v_max3_f32 v234, v234, v124, v125
	v_max3_f32 v0, v0, v123, v90
	v_max3_f32 v234, v234, v92, v93
	v_max3_f32 v0, v0, v91, v126
	v_max3_f32 v234, v234, v128, v129
	v_max3_f32 v0, v0, v127, v94
	v_max3_f32 v234, v234, v96, v97
	v_max3_f32 v0, v0, v95, v234
	v_max3_f32 v235, v98, v99, v100
	v_max3_f32 v236, v101, v102, v103
	v_max3_f32 v235, v235, v104, v105
	v_max3_f32 v236, v236, v106, v107
	v_max3_f32 v235, v235, v108, v109
	v_max3_f32 v236, v236, v110, v111
	v_max3_f32 v235, v235, v112, v113
	v_max3_f32 v236, v236, v66, v67
	v_max3_f32 v235, v235, v68, v69
	v_max3_f32 v236, v236, v70, v71
	v_max3_f32 v235, v235, v72, v73
	v_max3_f32 v236, v236, v74, v75
	v_max3_f32 v235, v235, v76, v77
	v_max3_f32 v236, v236, v78, v79
	v_max3_f32 v235, v235, v80, v81
	v_max_f32_e32 v235, v235, v236
	v_max_f32_e32 v236, v0, v235
	v_cmp_lt_f32_e32 vcc, 0x41000000, v236
	s_cmp_eq_u32 s9, 0
	s_cbranch_scc1 .Latt_rare
	s_cbranch_vccz .LBB0_1121
